# GEMM prologues: all 14 initial stage loads issued before the first wait (vmcnt(8) covers SB00/SA00/SB01 for the merged first phase)
# speedup vs baseline: 1.0075x; 1.0075x over previous
.LBB0_260:
	v_bfe_u32 v203, v202, 4, 2
	v_and_b32_e32 v151, 15, v202
	v_lshlrev_b32_e32 v148, 4, v203
	v_lshlrev_b32_e32 v13, 2, v202
	v_readlane_b32 s33, v246, 0
	s_and_b32 s50, s5, 3
	v_lshl_or_b32 v12, v151, 6, v148
	s_lshl_b32 s5, s6, 13
	v_and_b32_e32 v13, 32, v13
	s_add_i32 s11, s33, 0x18000
	v_bitop3_b32 v12, v12, s5, v13 bitop3:0xde
	v_lshlrev_b32_e32 v14, 6, v202
	s_movk_i32 s5, 0x3c0
	s_add_i32 s51, s11, s4
	s_mov_b64 s[18:19], 0x80
	s_lshl_b32 s60, s6, 6
	v_and_or_b32 v14, v14, s5, v148
	s_lshl_b32 s5, s50, 12
	v_lshl_add_u64 v[6:7], v[6:7], 0, s[18:19]
	s_mov_b32 m0, s51
	s_add_i32 s52, s51, 0x2000
	s_add_i32 s54, s44, 0x8000
	s_add_i32 s55, s44, 0xa000
	global_load_lds_dwordx4 v[6:7], off
	v_lshl_add_u64 v[4:5], v[4:5], 0, s[18:19]
	s_mov_b32 m0, s52
	s_add_u32 s6, s16, 0x40080
	global_load_lds_dwordx4 v[4:5], off
	v_lshl_add_u64 v[2:3], v[2:3], 0, s[18:19]
	s_mov_b32 m0, s54
	s_addc_u32 s7, s17, 0
	s_add_i32 s15, s33, 0x1c000
	global_load_lds_dwordx4 v[2:3], off
	v_lshl_add_u64 v[0:1], v[0:1], 0, s[18:19]
	s_mov_b32 m0, s55
	s_add_i32 s56, s15, s4
	global_load_lds_dwordx4 v[0:1], off
	v_lshl_add_u64 v[0:1], s[6:7], 0, v[144:145]
	s_mov_b32 m0, s56
	s_add_i32 s57, s56, 0x2000
	global_load_lds_dwordx4 v[0:1], off
	v_lshl_add_u64 v[0:1], s[6:7], 0, v[146:147]
	s_mov_b32 m0, s57
	v_readlane_b32 s6, v246, 1
	global_load_lds_dwordx4 v[0:1], off
	s_waitcnt vmcnt(8)
	s_barrier
	v_sub_co_u32_e64 v0, s[24:25], s50, 2
	s_nop 0
	v_readfirstlane_b32 s4, v0
	s_lshl_b32 s4, s4, 6
	v_or_b32_e32 v204, s60, v151
	v_bitop3_b32 v13, s5, v14, v13 bitop3:0xf6
	s_lshl_b32 s58, s50, 6
	s_ashr_i32 s5, s4, 31
	s_addk_i32 s60, 0x80
	s_ashr_i32 s61, s6, 31
	s_ashr_i32 s63, s30, 31
	s_add_u32 s26, s22, 0x192cc000
	s_addc_u32 s27, s23, 0
	s_lshl_b64 s[4:5], s[4:5], 1
	s_add_u32 s4, s22, s4
	v_and_b32_e32 v2, 7, v202
	v_ashrrev_i32_e32 v1, 31, v0
	s_addc_u32 s5, s23, s5
	v_or_b32_e32 v208, 0x4000, v2
	v_lshlrev_b64 v[0:1], 8, v[0:1]
	v_or_b32_e32 v209, 0xfff80000, v2
	v_lshl_add_u64 v[2:3], s[4:5], 0, v[148:149]
	s_mov_b64 s[4:5], 0x8d64000
	v_lshl_add_u64 v[152:153], v[2:3], 0, s[4:5]
	v_lshl_add_u64 v[0:1], s[20:21], 0, v[0:1]
	s_mov_b64 s[4:5], 0x9600000
	v_lshl_add_u64 v[154:155], v[0:1], 0, s[4:5]
	s_mov_b64 s[4:5], 0x8480000
	v_lshl_add_u64 v[156:157], v[0:1], 0, s[4:5]
	s_lshl_b32 s4, s50, 7
	s_add_u32 s4, s22, s4
	s_addc_u32 s5, s23, 0
	v_lshl_add_u64 v[0:1], s[4:5], 0, v[148:149]
	s_mov_b64 s[4:5], 0x8524000
	v_lshl_add_u64 v[158:159], v[0:1], 0, s[4:5]
	v_lshl_add_u64 v[0:1], s[22:23], 0, v[148:149]
	s_mov_b64 s[4:5], 0x6424000
	v_lshl_add_u64 v[160:161], v[0:1], 0, s[4:5]
	v_lshlrev_b32_e32 v0, 8, v202
	s_lshl_b32 s4, s50, 8
	v_and_b32_e32 v0, 0xffff8000, v0
	v_lshlrev_b32_e32 v1, 11, v10
	s_add_u32 s4, s20, s4
	v_or3_b32 v0, v8, v0, v1
	s_addc_u32 s5, s21, 0
	v_add_u32_e32 v162, v0, v9
	v_lshlrev_b32_e32 v0, 4, v11
	s_add_u32 s28, s4, 0x8e00000
	v_and_b32_e32 v0, 0xffff8000, v0
	s_waitcnt vmcnt(6)
	s_addc_u32 s29, s5, 0
	v_or3_b32 v0, v8, v0, v1
	v_lshlrev_b32_e32 v150, 3, v203
	s_add_u32 s30, s4, 0x8400000
	v_add_u32_e32 v164, v0, v9
	v_mbcnt_lo_u32_b32 v0, -1, 0
	s_mov_b32 s53, 0x8000
	v_or_b32_e32 v205, 16, v204
	v_or_b32_e32 v206, 32, v204
	v_or_b32_e32 v207, 48, v204
	s_mov_b32 s59, 0
	s_mov_b32 s62, s6
	s_addc_u32 s31, s5, 0
	v_or_b32_e32 v210, s58, v150
	v_mov_b32_e32 v163, v149
	v_mov_b32_e32 v165, v149
	v_mov_b64_e32 v[166:167], 0x5ab
	v_add_u32_e32 v211, s2, v13
	v_add_u32_e32 v212, s33, v12
	v_add_u32_e32 v213, s3, v13
	v_add_u32_e32 v214, s11, v13
	v_add_u32_e32 v215, s15, v13
	s_movk_i32 s64, 0xfdf
	s_movk_i32 s65, 0xfef
	s_movk_i32 s66, 0xfff
	v_mov_b32_e32 v216, 0x358637bd
	v_mov_b32_e32 v217, 0x3e000000
	v_mov_b32_e32 v218, 0x78
	v_mbcnt_hi_u32_b32 v219, -1, v0
	v_mov_b32_e32 v220, 0xfcf
	s_barrier
	v_readlane_b32 s7, v246, 2
	s_branch .LBB0_262

.LBB0_642:
	v_bfe_u32 v136, v202, 4, 2
	v_and_b32_e32 v12, 15, v202
	v_lshlrev_b32_e32 v13, 4, v136
	v_lshlrev_b32_e32 v14, 2, v202
	v_lshl_or_b32 v137, s8, 6, v12
	v_lshl_or_b32 v12, v12, 6, v13
	s_lshl_b32 s8, s8, 13
	v_and_b32_e32 v14, 32, v14
	s_and_b32 s26, s9, 3
	v_bitop3_b32 v12, v12, s8, v14 bitop3:0xde
	v_lshlrev_b32_e32 v15, 6, v202
	s_movk_i32 s8, 0x3c0
	v_readlane_b32 s45, v246, 0
	v_and_or_b32 v13, v15, s8, v13
	s_lshl_b32 s8, s26, 12
	s_add_i32 s47, s45, 0x18000
	v_bitop3_b32 v13, s8, v13, v14 bitop3:0xf6
	s_add_i32 s36, s47, s11
	s_mov_b64 s[8:9], 0x80
	v_lshl_add_u64 v[6:7], v[6:7], 0, s[8:9]
	s_mov_b32 m0, s36
	s_add_i32 s37, s36, 0x2000
	s_add_i32 s38, s29, 0x8000
	s_add_i32 s39, s29, 0xa000
	global_load_lds_dwordx4 v[6:7], off
	v_lshl_add_u64 v[4:5], v[4:5], 0, s[8:9]
	s_mov_b32 m0, s37
	s_add_u32 s16, s6, 0x40080
	global_load_lds_dwordx4 v[4:5], off
	v_lshl_add_u64 v[2:3], v[2:3], 0, s[8:9]
	s_mov_b32 m0, s38
	s_addc_u32 s17, s7, 0
	s_add_i32 s48, s45, 0x1c000
	global_load_lds_dwordx4 v[2:3], off
	v_lshl_add_u64 v[0:1], v[0:1], 0, s[8:9]
	s_mov_b32 m0, s39
	s_add_i32 s40, s48, s11
	global_load_lds_dwordx4 v[0:1], off
	v_lshl_add_u64 v[0:1], s[16:17], 0, v[130:131]
	s_mov_b32 m0, s40
	s_add_i32 s41, s40, 0x2000
	global_load_lds_dwordx4 v[0:1], off
	v_lshl_add_u64 v[0:1], s[16:17], 0, v[128:129]
	s_mov_b32 m0, s41
	s_lshl_b32 s10, s10, 19
	global_load_lds_dwordx4 v[0:1], off
	s_waitcnt vmcnt(8)
	s_barrier
	v_lshlrev_b32_e32 v0, 8, v202
	v_and_b32_e32 v0, 0xffff8000, v0
	v_lshlrev_b32_e32 v2, 11, v11
	s_add_u32 s10, s22, s10
	v_or3_b32 v0, v10, v0, v2
	s_addc_u32 s11, s23, 0
	v_add_u32_e32 v0, v0, v9
	v_mov_b32_e32 v1, v131
	v_lshl_add_u64 v[0:1], s[10:11], 0, v[0:1]
	s_mov_b64 s[16:17], 0x159e4080
	v_lshl_add_u64 v[132:133], v[0:1], 0, s[16:17]
	v_lshlrev_b32_e32 v0, 4, v8
	v_and_b32_e32 v0, 0xffff8000, v0
	v_or3_b32 v0, v10, v0, v2
	s_add_u32 s12, s22, s12
	s_waitcnt vmcnt(6)
	v_add_u32_e32 v0, v0, v9
	v_mov_b32_e32 v1, v131
	s_addc_u32 s13, s23, s13
	v_lshl_add_u64 v[0:1], s[10:11], 0, v[0:1]
	s_add_u32 s42, s12, 0x580100
	v_lshl_add_u64 v[134:135], v[0:1], 0, s[16:17]
	s_addc_u32 s43, s13, 0
	s_mov_b32 s44, -2
	s_mov_b64 s[12:13], 0
	v_add_u32_e32 v138, s14, v13
	v_add_u32_e32 v139, s45, v12
	s_add_i32 s45, s29, 0xc000
	s_add_i32 s46, s29, 0xe000
	v_add_u32_e32 v140, s15, v13
	v_add_u32_e32 v141, s47, v13
	v_add_u32_e32 v142, s48, v13
	v_mov_b32_e32 v0, v131
	v_mov_b32_e32 v1, v131
	v_mov_b32_e32 v2, v131
	v_mov_b32_e32 v3, v131
	v_mov_b32_e32 v4, v131
	v_mov_b32_e32 v5, v131
	v_mov_b32_e32 v6, v131
	v_mov_b32_e32 v7, v131
	v_mov_b32_e32 v16, v131
	v_mov_b32_e32 v17, v131
	v_mov_b32_e32 v18, v131
	v_mov_b32_e32 v19, v131
	v_mov_b32_e32 v20, v131
	s_waitcnt lgkmcnt(0)
	v_mov_b32_e32 v21, v131
	v_mov_b32_e32 v22, v131
	v_mov_b32_e32 v23, v131
	v_mov_b32_e32 v32, v131
	v_mov_b32_e32 v33, v131
	v_mov_b32_e32 v34, v131
	v_mov_b32_e32 v35, v131
	v_mov_b32_e32 v36, v131
	v_mov_b32_e32 v37, v131
	v_mov_b32_e32 v38, v131
	v_mov_b32_e32 v39, v131
	v_mov_b32_e32 v48, v131
	v_mov_b32_e32 v49, v131
	v_mov_b32_e32 v50, v131
	v_mov_b32_e32 v51, v131
	v_mov_b32_e32 v52, v131
	v_mov_b32_e32 v53, v131
	v_mov_b32_e32 v54, v131
	v_mov_b32_e32 v55, v131
	v_mov_b32_e32 v8, v131
	v_mov_b32_e32 v9, v131
	v_mov_b32_e32 v10, v131
	v_mov_b32_e32 v11, v131
	v_mov_b32_e32 v12, v131
	v_mov_b32_e32 v13, v131
	v_mov_b32_e32 v14, v131
	v_mov_b32_e32 v15, v131
	v_mov_b32_e32 v24, v131
	v_mov_b32_e32 v25, v131
	v_mov_b32_e32 v26, v131
	v_mov_b32_e32 v27, v131
	v_mov_b32_e32 v28, v131
	v_mov_b32_e32 v29, v131
	v_mov_b32_e32 v30, v131
	v_mov_b32_e32 v31, v131
	v_mov_b32_e32 v40, v131
	v_mov_b32_e32 v41, v131
	v_mov_b32_e32 v42, v131
	v_mov_b32_e32 v43, v131
	v_mov_b32_e32 v44, v131
	v_mov_b32_e32 v45, v131
	v_mov_b32_e32 v46, v131
	v_mov_b32_e32 v47, v131
	v_mov_b32_e32 v56, v131
	v_mov_b32_e32 v57, v131
	v_mov_b32_e32 v58, v131
	v_mov_b32_e32 v59, v131
	v_mov_b32_e32 v60, v131
	v_mov_b32_e32 v61, v131
	v_mov_b32_e32 v62, v131
	v_mov_b32_e32 v63, v131
	v_mov_b32_e32 v64, v131
	v_mov_b32_e32 v65, v131
	v_mov_b32_e32 v66, v131
	v_mov_b32_e32 v67, v131
	v_mov_b32_e32 v68, v131
	v_mov_b32_e32 v69, v131
	v_mov_b32_e32 v70, v131
	v_mov_b32_e32 v71, v131
	v_mov_b32_e32 v80, v131
	v_mov_b32_e32 v81, v131
	v_mov_b32_e32 v82, v131
	v_mov_b32_e32 v83, v131
	v_mov_b32_e32 v84, v131
	v_mov_b32_e32 v85, v131
	v_mov_b32_e32 v86, v131
	v_mov_b32_e32 v87, v131
	v_mov_b32_e32 v96, v131
	v_mov_b32_e32 v97, v131
	v_mov_b32_e32 v98, v131
	v_mov_b32_e32 v99, v131
	v_mov_b32_e32 v100, v131
	v_mov_b32_e32 v101, v131
	v_mov_b32_e32 v102, v131
	v_mov_b32_e32 v103, v131
	v_mov_b32_e32 v112, v131
	v_mov_b32_e32 v113, v131
	v_mov_b32_e32 v114, v131
	v_mov_b32_e32 v115, v131
	v_mov_b32_e32 v116, v131
	v_mov_b32_e32 v117, v131
	v_mov_b32_e32 v118, v131
	v_mov_b32_e32 v119, v131
	v_mov_b32_e32 v72, v131
	v_mov_b32_e32 v73, v131
	v_mov_b32_e32 v74, v131
	v_mov_b32_e32 v75, v131
	v_mov_b32_e32 v76, v131
	v_mov_b32_e32 v77, v131
	v_mov_b32_e32 v78, v131
	v_mov_b32_e32 v79, v131
	v_mov_b32_e32 v88, v131
	v_mov_b32_e32 v89, v131
	v_mov_b32_e32 v90, v131
	v_mov_b32_e32 v91, v131
	v_mov_b32_e32 v92, v131
	v_mov_b32_e32 v93, v131
	v_mov_b32_e32 v94, v131
	v_mov_b32_e32 v95, v131
	v_mov_b32_e32 v104, v131
	v_mov_b32_e32 v105, v131
	v_mov_b32_e32 v106, v131
	v_mov_b32_e32 v107, v131
	v_mov_b32_e32 v108, v131
	v_mov_b32_e32 v109, v131
	v_mov_b32_e32 v110, v131
	v_mov_b32_e32 v111, v131
	v_mov_b32_e32 v120, v131
	v_mov_b32_e32 v121, v131
	v_mov_b32_e32 v122, v131
	v_mov_b32_e32 v123, v131
	v_mov_b32_e32 v124, v131
	v_mov_b32_e32 v125, v131
	v_mov_b32_e32 v126, v131
	v_mov_b32_e32 v127, v131
	s_barrier
	s_waitcnt vmcnt(0)

.LBB0_773:
	v_bfe_u32 v141, v202, 4, 2
	v_and_b32_e32 v139, 15, v202
	v_lshlrev_b32_e32 v138, 4, v141
	v_lshlrev_b32_e32 v13, 2, v202
	v_lshl_or_b32 v142, s6, 6, v139
	v_lshl_or_b32 v12, v139, 6, v138
	s_lshl_b32 s6, s6, 13
	v_and_b32_e32 v13, 32, v13
	s_and_b32 s17, s7, 3
	v_bitop3_b32 v12, v12, s6, v13 bitop3:0xde
	v_lshlrev_b32_e32 v14, 6, v202
	s_movk_i32 s6, 0x3c0
	v_readlane_b32 s41, v246, 0
	v_and_or_b32 v14, v14, s6, v138
	s_lshl_b32 s6, s17, 12
	s_add_i32 s43, s41, 0x18000
	v_bitop3_b32 v13, s6, v14, v13 bitop3:0xf6
	s_add_i32 s31, s43, s9
	s_mov_b64 s[6:7], 0x80
	v_lshl_add_u64 v[6:7], v[6:7], 0, s[6:7]
	s_mov_b32 m0, s31
	s_add_i32 s33, s31, 0x2000
	s_add_i32 s34, s25, 0x8000
	s_add_i32 s35, s25, 0xa000
	global_load_lds_dwordx4 v[6:7], off
	v_lshl_add_u64 v[4:5], v[4:5], 0, s[6:7]
	s_mov_b32 m0, s33
	s_add_u32 s14, s4, 0x40080
	global_load_lds_dwordx4 v[4:5], off
	v_lshl_add_u64 v[2:3], v[2:3], 0, s[6:7]
	s_mov_b32 m0, s34
	s_addc_u32 s15, s5, 0
	s_add_i32 s44, s41, 0x1c000
	global_load_lds_dwordx4 v[2:3], off
	v_lshl_add_u64 v[0:1], v[0:1], 0, s[6:7]
	s_mov_b32 m0, s35
	s_add_i32 s36, s44, s9
	global_load_lds_dwordx4 v[0:1], off
	v_lshl_add_u64 v[0:1], s[14:15], 0, v[132:133]
	s_mov_b32 m0, s36
	s_add_i32 s37, s36, 0x2000
	global_load_lds_dwordx4 v[0:1], off
	v_lshl_add_u64 v[0:1], s[14:15], 0, v[130:131]
	s_mov_b32 m0, s37
	s_lshl_b32 s8, s8, 19
	global_load_lds_dwordx4 v[0:1], off
	s_waitcnt vmcnt(8)
	s_barrier
	v_lshlrev_b32_e32 v0, 8, v202
	v_and_b32_e32 v0, 0xffff8000, v0
	v_lshlrev_b32_e32 v2, 11, v11
	s_add_u32 s8, s22, s8
	v_or3_b32 v0, v10, v0, v2
	s_addc_u32 s9, s23, 0
	v_add_u32_e32 v0, v0, v9
	v_mov_b32_e32 v1, v133
	v_lshl_add_u64 v[0:1], s[8:9], 0, v[0:1]
	s_mov_b64 s[14:15], 0x5c40080
	v_lshl_add_u64 v[134:135], v[0:1], 0, s[14:15]
	v_lshlrev_b32_e32 v0, 4, v8
	v_and_b32_e32 v0, 0xffff8000, v0
	v_or3_b32 v0, v10, v0, v2
	s_add_u32 s10, s22, s10
	s_waitcnt vmcnt(6)
	v_add_u32_e32 v0, v0, v9
	v_mov_b32_e32 v1, v133
	s_addc_u32 s11, s23, s11
	v_lshl_add_u64 v[0:1], s[8:9], 0, v[0:1]
	s_add_u32 s38, s10, 0x780100
	v_lshrrev_b32_e32 v140, 2, v202
	v_lshl_add_u64 v[136:137], v[0:1], 0, s[14:15]
	s_addc_u32 s39, s11, 0
	s_mov_b32 s40, -2
	s_mov_b64 s[10:11], 0
	v_add_u32_e32 v143, s12, v13
	v_add_u32_e32 v144, s41, v12
	s_add_i32 s41, s25, 0xc000
	s_add_i32 s42, s25, 0xe000
	v_add_u32_e32 v145, s13, v13
	v_add_u32_e32 v146, s43, v13
	v_add_u32_e32 v147, s44, v13
	v_mov_b32_e32 v0, v133
	v_mov_b32_e32 v1, v133
	v_mov_b32_e32 v2, v133
	v_mov_b32_e32 v3, v133
	v_mov_b32_e32 v4, v133
	v_mov_b32_e32 v5, v133
	v_mov_b32_e32 v6, v133
	v_mov_b32_e32 v7, v133
	v_mov_b32_e32 v16, v133
	v_mov_b32_e32 v17, v133
	v_mov_b32_e32 v18, v133
	v_mov_b32_e32 v19, v133
	v_mov_b32_e32 v20, v133
	v_mov_b32_e32 v21, v133
	v_mov_b32_e32 v22, v133
	v_mov_b32_e32 v23, v133
	v_mov_b32_e32 v32, v133
	v_mov_b32_e32 v33, v133
	v_mov_b32_e32 v34, v133
	v_mov_b32_e32 v35, v133
	v_mov_b32_e32 v36, v133
	v_mov_b32_e32 v37, v133
	v_mov_b32_e32 v38, v133
	v_mov_b32_e32 v39, v133
	v_mov_b32_e32 v48, v133
	v_mov_b32_e32 v49, v133
	v_mov_b32_e32 v50, v133
	v_mov_b32_e32 v51, v133
	v_mov_b32_e32 v52, v133
	v_mov_b32_e32 v53, v133
	v_mov_b32_e32 v54, v133
	v_mov_b32_e32 v55, v133
	v_mov_b32_e32 v8, v133
	v_mov_b32_e32 v9, v133
	v_mov_b32_e32 v10, v133
	v_mov_b32_e32 v11, v133
	v_mov_b32_e32 v12, v133
	v_mov_b32_e32 v13, v133
	v_mov_b32_e32 v14, v133
	v_mov_b32_e32 v15, v133
	v_mov_b32_e32 v24, v133
	v_mov_b32_e32 v25, v133
	v_mov_b32_e32 v26, v133
	v_mov_b32_e32 v27, v133
	v_mov_b32_e32 v28, v133
	v_mov_b32_e32 v29, v133
	v_mov_b32_e32 v30, v133
	v_mov_b32_e32 v31, v133
	v_mov_b32_e32 v40, v133
	v_mov_b32_e32 v41, v133
	v_mov_b32_e32 v42, v133
	v_mov_b32_e32 v43, v133
	v_mov_b32_e32 v44, v133
	v_mov_b32_e32 v45, v133
	v_mov_b32_e32 v46, v133
	v_mov_b32_e32 v47, v133
	v_mov_b32_e32 v56, v133
	v_mov_b32_e32 v57, v133
	v_mov_b32_e32 v58, v133
	v_mov_b32_e32 v59, v133
	v_mov_b32_e32 v60, v133
	v_mov_b32_e32 v61, v133
	v_mov_b32_e32 v62, v133
	v_mov_b32_e32 v63, v133
	v_mov_b32_e32 v64, v133
	v_mov_b32_e32 v65, v133
	v_mov_b32_e32 v66, v133
	v_mov_b32_e32 v67, v133
	v_mov_b32_e32 v68, v133
	v_mov_b32_e32 v69, v133
	v_mov_b32_e32 v70, v133
	v_mov_b32_e32 v71, v133
	v_mov_b32_e32 v80, v133
	v_mov_b32_e32 v81, v133
	v_mov_b32_e32 v82, v133
	v_mov_b32_e32 v83, v133
	v_mov_b32_e32 v84, v133
	v_mov_b32_e32 v85, v133
	v_mov_b32_e32 v86, v133
	v_mov_b32_e32 v87, v133
	v_mov_b32_e32 v96, v133
	v_mov_b32_e32 v97, v133
	v_mov_b32_e32 v98, v133
	v_mov_b32_e32 v99, v133
	v_mov_b32_e32 v100, v133
	v_mov_b32_e32 v101, v133
	v_mov_b32_e32 v102, v133
	v_mov_b32_e32 v103, v133
	v_mov_b32_e32 v112, v133
	v_mov_b32_e32 v113, v133
	v_mov_b32_e32 v114, v133
	v_mov_b32_e32 v115, v133
	v_mov_b32_e32 v116, v133
	v_mov_b32_e32 v117, v133
	v_mov_b32_e32 v118, v133
	v_mov_b32_e32 v119, v133
	v_mov_b32_e32 v72, v133
	v_mov_b32_e32 v73, v133
	v_mov_b32_e32 v74, v133
	v_mov_b32_e32 v75, v133
	v_mov_b32_e32 v76, v133
	v_mov_b32_e32 v77, v133
	v_mov_b32_e32 v78, v133
	v_mov_b32_e32 v79, v133
	v_mov_b32_e32 v88, v133
	v_mov_b32_e32 v89, v133
	v_mov_b32_e32 v90, v133
	v_mov_b32_e32 v91, v133
	v_mov_b32_e32 v92, v133
	v_mov_b32_e32 v93, v133
	v_mov_b32_e32 v94, v133
	v_mov_b32_e32 v95, v133
	v_mov_b32_e32 v104, v133
	v_mov_b32_e32 v105, v133
	v_mov_b32_e32 v106, v133
	v_mov_b32_e32 v107, v133
	v_mov_b32_e32 v108, v133
	v_mov_b32_e32 v109, v133
	v_mov_b32_e32 v110, v133
	v_mov_b32_e32 v111, v133
	v_mov_b32_e32 v120, v133
	v_mov_b32_e32 v121, v133
	v_mov_b32_e32 v122, v133
	v_mov_b32_e32 v123, v133
	v_mov_b32_e32 v124, v133
	v_mov_b32_e32 v125, v133
	v_mov_b32_e32 v126, v133
	v_mov_b32_e32 v127, v133
	s_barrier
	s_waitcnt vmcnt(0)

.LBB0_876:
	s_add_u32 s10, s22, 0x1c00000
	s_addc_u32 s11, s23, 0
	s_add_u32 s51, s22, 0x18ba4000
	v_readlane_b32 s31, v246, 0
	s_addc_u32 s52, s23, 0
	s_add_i32 s19, s31, 0x18000
	s_and_b32 s53, s9, 3
	s_add_i32 s54, s19, s5
	s_mov_b64 s[12:13], 0x80
	s_lshl_b32 s9, s4, 13
	s_lshl_b32 s18, s53, 12
	v_lshl_add_u64 v[6:7], v[6:7], 0, s[12:13]
	s_mov_b32 m0, s54
	s_add_i32 s55, s54, 0x2000
	s_add_i32 s56, s45, 0x8000
	s_add_i32 s57, s45, 0xa000
	global_load_lds_dwordx4 v[6:7], off
	v_lshl_add_u64 v[4:5], v[4:5], 0, s[12:13]
	s_mov_b32 m0, s55
	s_add_u32 s16, s28, 0x40080
	global_load_lds_dwordx4 v[4:5], off
	v_lshl_add_u64 v[2:3], v[2:3], 0, s[12:13]
	s_mov_b32 m0, s56
	s_addc_u32 s17, s29, 0
	s_add_i32 s25, s31, 0x1c000
	global_load_lds_dwordx4 v[2:3], off
	v_lshl_add_u64 v[0:1], v[0:1], 0, s[12:13]
	s_mov_b32 m0, s57
	s_add_i32 s58, s25, s5
	global_load_lds_dwordx4 v[0:1], off
	v_lshl_add_u64 v[0:1], s[16:17], 0, v[160:161]
	s_mov_b32 m0, s58
	s_add_i32 s59, s58, 0x2000
	global_load_lds_dwordx4 v[0:1], off
	v_lshl_add_u64 v[0:1], s[16:17], 0, v[162:163]
	s_mov_b32 m0, s59
	v_lshlrev_b32_e32 v5, 6, v202
	global_load_lds_dwordx4 v[0:1], off
	s_waitcnt vmcnt(8)
	s_barrier
	v_bfe_u32 v0, v202, 4, 2
	v_and_b32_e32 v1, 15, v202
	s_waitcnt vmcnt(0)
	v_lshl_or_b32 v184, s4, 6, v1
	v_lshlrev_b32_e32 v3, 4, v0
	s_movk_i32 s4, 0x3c0
	v_lshlrev_b32_e32 v2, 3, v0
	v_lshl_or_b32 v1, v1, 6, v3
	v_and_or_b32 v3, v5, s4, v3
	v_cmp_eq_u32_e64 s[4:5], 0, v0
	v_lshlrev_b32_e32 v0, 8, v202
	v_lshl_or_b32 v185, s53, 6, v2
	v_and_b32_e32 v0, 0xffff8000, v0
	v_lshlrev_b32_e32 v2, 11, v10
	v_or3_b32 v0, v8, v0, v2
	v_add_u32_e32 v164, v0, v9
	v_lshlrev_b32_e32 v0, 4, v11
	v_lshlrev_b32_e32 v4, 2, v202
	v_and_b32_e32 v0, 0xffff8000, v0
	v_and_b32_e32 v4, 32, v4
	s_waitcnt vmcnt(6)
	v_or3_b32 v0, v8, v0, v2
	v_bitop3_b32 v1, v1, s9, v4 bitop3:0xde
	v_bitop3_b32 v3, s18, v3, v4 bitop3:0xf6
	s_mov_b32 s9, 0
	v_readlane_b32 s16, v246, 1
	v_add_u32_e32 v166, v0, v9
	v_mbcnt_lo_u32_b32 v0, -1, 0
	v_readlane_b32 s17, v246, 2
	s_ashr_i32 s60, s16, 31
	s_mov_b32 s61, s16
	s_ashr_i32 s62, s30, 31
	s_lshr_b32 s63, s33, 1
	v_mov_b32_e32 v165, v161
	v_mov_b32_e32 v167, v161
	v_mov_b64_e32 v[168:169], s[8:9]
	v_add_u32_e32 v186, s14, v3
	v_add_u32_e32 v187, s31, v1
	v_add_u32_e32 v188, s15, v3
	v_add_u32_e32 v189, s19, v3
	v_add_u32_e32 v190, s25, v3
	v_mbcnt_hi_u32_b32 v191, -1, v0
	s_barrier
	s_branch .LBB0_878

.LBB0_965:
	s_add_u32 s10, s22, 0x195cc000
	s_addc_u32 s11, s23, 0
	s_add_u32 s51, s22, 0x18fc4000
	v_readlane_b32 s31, v246, 0
	s_addc_u32 s52, s23, 0
	s_add_i32 s19, s31, 0x18000
	s_and_b32 s53, s9, 3
	s_add_i32 s54, s19, s5
	s_mov_b64 s[12:13], 0x80
	s_lshl_b32 s9, s4, 13
	s_lshl_b32 s18, s53, 12
	v_lshl_add_u64 v[6:7], v[6:7], 0, s[12:13]
	s_mov_b32 m0, s54
	s_add_i32 s55, s54, 0x2000
	s_add_i32 s56, s45, 0x8000
	s_add_i32 s57, s45, 0xa000
	global_load_lds_dwordx4 v[6:7], off
	v_lshl_add_u64 v[4:5], v[4:5], 0, s[12:13]
	s_mov_b32 m0, s55
	s_add_u32 s16, s28, 0x40080
	global_load_lds_dwordx4 v[4:5], off
	v_lshl_add_u64 v[2:3], v[2:3], 0, s[12:13]
	s_mov_b32 m0, s56
	s_addc_u32 s17, s29, 0
	s_add_i32 s25, s31, 0x1c000
	global_load_lds_dwordx4 v[2:3], off
	v_lshl_add_u64 v[0:1], v[0:1], 0, s[12:13]
	s_mov_b32 m0, s57
	s_add_i32 s58, s25, s5
	global_load_lds_dwordx4 v[0:1], off
	v_lshl_add_u64 v[0:1], s[16:17], 0, v[128:129]
	s_mov_b32 m0, s58
	s_add_i32 s59, s58, 0x2000
	global_load_lds_dwordx4 v[0:1], off
	v_lshl_add_u64 v[0:1], s[16:17], 0, v[130:131]
	s_mov_b32 m0, s59
	v_lshlrev_b32_e32 v4, 2, v202
	global_load_lds_dwordx4 v[0:1], off
	s_waitcnt vmcnt(8)
	s_barrier
	v_bfe_u32 v1, v202, 4, 2
	v_and_b32_e32 v0, 15, v202
	v_lshlrev_b32_e32 v3, 4, v1
	v_lshl_or_b32 v144, s4, 6, v0
	v_lshl_or_b32 v0, v0, 6, v3
	v_and_b32_e32 v4, 32, v4
	v_bitop3_b32 v5, v0, s9, v4 bitop3:0xde
	v_lshlrev_b32_e32 v0, 6, v202
	s_movk_i32 s4, 0x3c0
	v_and_or_b32 v0, v0, s4, v3
	v_bitop3_b32 v3, s18, v0, v4 bitop3:0xf6
	v_mul_u32_u24_e32 v0, 0x21000, v1
	v_readlane_b32 s16, v246, 1
	v_lshlrev_b32_e32 v2, 3, v1
	v_cmp_eq_u32_e64 s[4:5], 0, v1
	v_readlane_b32 s17, v246, 2
	v_lshlrev_b32_e32 v0, 2, v0
	v_mov_b32_e32 v1, v129
	s_ashr_i32 s61, s16, 31
	s_mov_b32 s62, s16
	v_lshl_add_u64 v[0:1], s[22:23], 0, v[0:1]
	s_mov_b64 s[16:17], 0x18ba4000
	v_lshl_add_u64 v[132:133], v[0:1], 0, s[16:17]
	v_lshlrev_b32_e32 v0, 8, v202
	v_and_b32_e32 v0, 0xffff8000, v0
	v_lshlrev_b32_e32 v1, 11, v10
	v_or3_b32 v0, v8, v0, v1
	v_add_u32_e32 v134, v0, v9
	v_lshlrev_b32_e32 v0, 4, v11
	v_and_b32_e32 v0, 0xffff8000, v0
	s_waitcnt vmcnt(6)
	v_or3_b32 v0, v8, v0, v1
	s_mov_b32 s9, 0
	v_add_u32_e32 v136, v0, v9
	v_mbcnt_lo_u32_b32 v0, -1, 0
	s_mov_b32 s60, 0x21000
	v_lshl_or_b32 v145, s53, 6, v2
	s_ashr_i32 s63, s30, 31
	s_lshr_b32 s64, s33, 2
	v_mov_b32_e32 v135, v129
	v_mov_b32_e32 v137, v129
	v_mov_b64_e32 v[138:139], s[8:9]
	v_add_u32_e32 v146, s14, v3
	v_add_u32_e32 v147, s31, v5
	v_add_u32_e32 v148, s15, v3
	v_add_u32_e32 v149, s19, v3
	v_add_u32_e32 v150, s25, v3
	v_mbcnt_hi_u32_b32 v151, -1, v0
	s_mov_b32 s65, 0x42000
	s_mov_b32 s66, 0x63000
	v_mov_b32_e32 v152, 0x358637bd
	s_barrier
	s_branch .LBB0_967

.LBB0_1121:
	s_add_u32 s8, s22, 0x1c00000
	s_addc_u32 s9, s23, 0
	s_add_u32 s48, s22, 0x18db4000
	v_readlane_b32 s29, v246, 0
	s_addc_u32 s49, s23, 0
	s_add_i32 s19, s29, 0x18000
	s_and_b32 s50, s10, 3
	s_add_i32 s51, s19, s5
	s_mov_b64 s[10:11], 0x80
	s_lshl_b32 s16, s4, 13
	s_lshl_b32 s17, s50, 12
	v_lshl_add_u64 v[6:7], v[6:7], 0, s[10:11]
	s_mov_b32 m0, s51
	s_add_i32 s52, s51, 0x2000
	s_add_i32 s53, s42, 0x8000
	s_add_i32 s54, s42, 0xa000
	global_load_lds_dwordx4 v[6:7], off
	v_lshl_add_u64 v[4:5], v[4:5], 0, s[10:11]
	s_mov_b32 m0, s52
	s_add_u32 s14, s26, 0x20080
	global_load_lds_dwordx4 v[4:5], off
	v_lshl_add_u64 v[2:3], v[2:3], 0, s[10:11]
	s_mov_b32 m0, s53
	s_addc_u32 s15, s27, 0
	s_add_i32 s28, s29, 0x1c000
	global_load_lds_dwordx4 v[2:3], off
	v_lshl_add_u64 v[0:1], v[0:1], 0, s[10:11]
	s_mov_b32 m0, s54
	s_add_i32 s55, s28, s5
	global_load_lds_dwordx4 v[0:1], off
	v_lshl_add_u64 v[0:1], s[14:15], 0, v[160:161]
	s_mov_b32 m0, s55
	s_add_i32 s56, s55, 0x2000
	global_load_lds_dwordx4 v[0:1], off
	v_lshl_add_u64 v[0:1], s[14:15], 0, v[162:163]
	s_mov_b32 m0, s56
	v_lshlrev_b32_e32 v5, 6, v202
	global_load_lds_dwordx4 v[0:1], off
	s_waitcnt vmcnt(8)
	s_barrier
	v_bfe_u32 v0, v202, 4, 2
	v_and_b32_e32 v1, 15, v202
	s_waitcnt vmcnt(0)
	v_lshl_or_b32 v184, s4, 6, v1
	v_lshlrev_b32_e32 v3, 4, v0
	s_movk_i32 s4, 0x3c0
	v_lshlrev_b32_e32 v2, 3, v0
	v_lshl_or_b32 v1, v1, 6, v3
	v_and_or_b32 v3, v5, s4, v3
	v_cmp_eq_u32_e64 s[4:5], 0, v0
	v_lshlrev_b32_e32 v0, 7, v202
	v_lshl_or_b32 v185, s50, 6, v2
	v_and_b32_e32 v0, 0xffffc000, v0
	v_lshlrev_b32_e32 v2, 10, v10
	v_or3_b32 v0, v8, v0, v2
	v_add_u32_e32 v164, v0, v9
	v_lshlrev_b32_e32 v0, 3, v11
	v_lshlrev_b32_e32 v4, 2, v202
	v_and_b32_e32 v0, 0xffffc000, v0
	v_and_b32_e32 v4, 32, v4
	s_waitcnt vmcnt(6)
	v_or3_b32 v0, v8, v0, v2
	v_bitop3_b32 v1, v1, s16, v4 bitop3:0xde
	v_bitop3_b32 v3, s17, v3, v4 bitop3:0xf6
	v_readlane_b32 s14, v246, 1
	v_add_u32_e32 v166, v0, v9
	v_mbcnt_lo_u32_b32 v0, -1, 0
	s_mov_b32 s57, 0
	v_readlane_b32 s15, v246, 2
	s_ashr_i32 s58, s14, 31
	s_mov_b32 s59, s14
	s_ashr_i32 s60, s30, 31
	v_mov_b32_e32 v165, v161
	v_mov_b32_e32 v167, v161
	v_mov_b64_e32 v[168:169], 0x20f
	s_movk_i32 s61, 0x43
	v_add_u32_e32 v186, s12, v3
	v_add_u32_e32 v187, s29, v1
	v_add_u32_e32 v188, s13, v3
	v_add_u32_e32 v189, s19, v3
	v_add_u32_e32 v190, s28, v3
	v_mbcnt_hi_u32_b32 v191, -1, v0
	s_barrier
	s_branch .LBB0_1123

.LBB0_1224:
	v_readlane_b32 s27, v246, 0
	s_lshl_b32 s12, s12, 5
	s_add_i32 s25, s27, 0x18000
	s_and_b32 s24, s12, 0x60
	s_add_i32 s54, s25, s5
	s_mov_b64 s[12:13], 0x80
	s_lshl_b32 s17, s4, 13
	s_lshl_b32 s18, s24, 7
	v_lshl_add_u64 v[6:7], v[6:7], 0, s[12:13]
	s_mov_b32 m0, s54
	s_add_i32 s55, s54, 0x2000
	s_add_i32 s56, s48, 0x8000
	s_add_i32 s57, s48, 0xa000
	global_load_lds_dwordx4 v[6:7], off
	v_lshl_add_u64 v[4:5], v[4:5], 0, s[12:13]
	s_mov_b32 m0, s55
	s_add_u32 s14, s34, 0x40080
	global_load_lds_dwordx4 v[4:5], off
	v_lshl_add_u64 v[2:3], v[2:3], 0, s[12:13]
	s_mov_b32 m0, s56
	s_addc_u32 s15, s35, 0
	s_add_i32 s26, s27, 0x1c000
	global_load_lds_dwordx4 v[2:3], off
	v_lshl_add_u64 v[0:1], v[0:1], 0, s[12:13]
	s_mov_b32 m0, s57
	s_add_i32 s58, s26, s5
	global_load_lds_dwordx4 v[0:1], off
	v_lshl_add_u64 v[0:1], s[14:15], 0, v[128:129]
	s_mov_b32 m0, s58
	s_add_i32 s59, s58, 0x2000
	global_load_lds_dwordx4 v[0:1], off
	v_lshl_add_u64 v[0:1], s[14:15], 0, v[130:131]
	s_mov_b32 m0, s59
	v_bfe_u32 v2, v202, 4, 2
	global_load_lds_dwordx4 v[0:1], off
	s_waitcnt vmcnt(8)
	s_barrier
	v_lshlrev_b32_e32 v0, 4, v2
	v_lshlrev_b32_e32 v3, 2, v153
	v_lshl_or_b32 v1, v153, 6, v0
	v_and_b32_e32 v3, 32, v3
	v_or_b32_e32 v0, v0, v151
	v_bitop3_b32 v3, v1, s17, v3 bitop3:0xde
	v_bitop3_b32 v4, s18, v0, v155 bitop3:0xf6
	v_mul_u32_u24_e32 v0, 0x21000, v2
	v_and_b32_e32 v1, 63, v202
	v_lshl_or_b32 v160, s4, 6, v153
	v_cmp_eq_u32_e64 s[4:5], 0, v1
	v_lshlrev_b32_e32 v0, 2, v0
	v_mov_b32_e32 v1, v129
	v_lshl_add_u64 v[0:1], s[22:23], 0, v[0:1]
	s_mov_b64 s[18:19], 0x18db4000
	v_lshl_add_u64 v[132:133], v[0:1], 0, s[18:19]
	v_lshlrev_b32_e32 v0, 8, v202
	v_and_b32_e32 v0, 0xffff8000, v0
	v_lshlrev_b32_e32 v1, 11, v9
	v_or3_b32 v0, v147, v0, v1
	v_readlane_b32 s14, v246, 1
	v_add_u32_e32 v134, v0, v149
	v_lshlrev_b32_e32 v0, 4, v8
	s_ashr_i32 s61, s14, 31
	s_ashr_i32 s63, s74, 31
	v_and_b32_e32 v0, 0xffff8000, v0
	s_waitcnt vmcnt(6)
	v_readlane_b32 s15, v246, 2
	s_cmpk_gt_i32 s74, 0xef
	v_or3_b32 v0, v147, v0, v1
	s_mov_b32 s62, s14
	s_cselect_b64 s[14:15], -1, 0
	s_add_i32 s43, s74, 0xffffff10
	v_add_u32_e32 v136, v0, v149
	v_mbcnt_lo_u32_b32 v0, -1, 0
	s_mov_b32 s60, 0x21000
	s_mul_hi_u32 s64, s43, 9
	s_mul_i32 s65, s43, 9
	v_lshl_or_b32 v161, v2, 3, s24
	v_mov_b32_e32 v135, v129
	v_mov_b32_e32 v137, v129
	v_add_u32_e32 v162, s11, v4
	v_add_u32_e32 v163, s27, v3
	v_add_u32_e32 v164, s16, v4
	v_add_u32_e32 v165, s25, v4
	v_add_u32_e32 v166, s26, v4
	v_mbcnt_hi_u32_b32 v167, -1, v0
	s_mov_b32 s66, 0x42000
	s_mov_b32 s67, 0x63000
	s_waitcnt vmcnt(0)
	v_mov_b32_e32 v168, 0x358637bd
	v_readlane_b32 s92, v246, 0
	v_lshrrev_b32_e32 v203, 6, v202
	v_and_b32_e32 v247, 31, v202
	v_lshl_or_b32 v247, v203, 5, v247
	v_lshlrev_b32_e32 v247, 2, v247
	v_and_b32_e32 v203, 32, v202
	v_mul_u32_u24_e32 v203, 0x8400, v203
	v_add_u32_e32 v203, v203, v247
	s_add_i32 s92, s92, 0x20000
	s_nop 0
	v_add_u32_e32 v247, s92, v247
	s_movk_i32 s68, 0x1600
	v_mov_b64_e32 v[138:139], 0xac8
	v_mov_b64_e32 v[140:141], 0x57
	v_mov_b64_e32 v[142:143], 0xaff
	s_mov_b32 s11, 0
	s_barrier
	s_branch .LBB0_1227

.LBB0_1267:
	v_lshrrev_b32_e32 v10, 1, v202
	v_and_b32_e32 v137, 24, v10
	v_lshlrev_b32_e32 v10, 1, v137
	v_lshlrev_b32_e32 v12, 2, v153
	s_and_b32 s34, s9, 3
	v_lshl_or_b32 v136, s8, 6, v153
	v_lshl_or_b32 v11, v153, 6, v10
	s_lshl_b32 s8, s8, 13
	v_and_b32_e32 v12, 32, v12
	v_readlane_b32 s44, v246, 0
	v_bitop3_b32 v11, v11, s8, v12 bitop3:0xde
	v_or_b32_e32 v10, v10, v151
	s_lshl_b32 s8, s34, 12
	s_add_i32 s46, s44, 0x18000
	v_bitop3_b32 v10, s8, v10, v155 bitop3:0xf6
	s_add_i32 s35, s46, s11
	s_mov_b64 s[8:9], 0x80
	v_lshl_add_u64 v[6:7], v[6:7], 0, s[8:9]
	s_mov_b32 m0, s35
	s_add_i32 s36, s35, 0x2000
	s_add_i32 s37, s27, 0x8000
	s_add_i32 s38, s27, 0xa000
	global_load_lds_dwordx4 v[6:7], off
	v_lshl_add_u64 v[4:5], v[4:5], 0, s[8:9]
	s_mov_b32 m0, s36
	s_add_u32 s16, s6, 0xb0080
	global_load_lds_dwordx4 v[4:5], off
	v_lshl_add_u64 v[2:3], v[2:3], 0, s[8:9]
	s_mov_b32 m0, s37
	s_addc_u32 s17, s7, 0
	s_add_i32 s47, s44, 0x1c000
	global_load_lds_dwordx4 v[2:3], off
	v_lshl_add_u64 v[0:1], v[0:1], 0, s[8:9]
	s_mov_b32 m0, s38
	s_add_i32 s39, s47, s11
	global_load_lds_dwordx4 v[0:1], off
	v_lshl_add_u64 v[0:1], s[16:17], 0, v[130:131]
	s_mov_b32 m0, s39
	s_add_i32 s40, s39, 0x2000
	global_load_lds_dwordx4 v[0:1], off
	v_lshl_add_u64 v[0:1], s[16:17], 0, v[128:129]
	s_mov_b32 m0, s40
	s_mul_i32 s10, s10, 0x160000
	global_load_lds_dwordx4 v[0:1], off
	s_waitcnt vmcnt(8)
	s_barrier
	s_add_u32 s10, s22, s10
	s_addc_u32 s11, s23, 0
	v_add3_u32 v0, v9, v147, v149
	v_mov_b32_e32 v1, v131
	v_lshl_add_u64 v[0:1], s[10:11], 0, v[0:1]
	s_mov_b64 s[16:17], 0x114d4080
	s_add_u32 s12, s22, s12
	s_waitcnt vmcnt(6)
	v_lshl_add_u64 v[132:133], v[0:1], 0, s[16:17]
	v_add3_u32 v0, v8, v147, v149
	v_mov_b32_e32 v1, v131
	s_addc_u32 s13, s23, 0
	v_lshl_add_u64 v[0:1], s[10:11], 0, v[0:1]
	s_add_u32 s41, s12, 0x1680100
	v_lshl_add_u64 v[134:135], v[0:1], 0, s[16:17]
	s_addc_u32 s42, s13, 0
	s_mov_b32 s43, -2
	s_mov_b64 s[12:13], 0
	v_add_u32_e32 v138, s14, v10
	v_add_u32_e32 v139, s44, v11
	s_add_i32 s44, s27, 0xc000
	s_add_i32 s45, s27, 0xe000
	v_add_u32_e32 v140, s15, v10
	v_add_u32_e32 v141, s46, v10
	v_add_u32_e32 v142, s47, v10
	v_mov_b32_e32 v0, v131
	v_mov_b32_e32 v1, v131
	v_mov_b32_e32 v2, v131
	v_mov_b32_e32 v3, v131
	v_mov_b32_e32 v4, v131
	v_mov_b32_e32 v5, v131
	v_mov_b32_e32 v6, v131
	v_mov_b32_e32 v7, v131
	v_mov_b32_e32 v16, v131
	v_mov_b32_e32 v17, v131
	v_mov_b32_e32 v18, v131
	v_mov_b32_e32 v19, v131
	v_mov_b32_e32 v20, v131
	v_mov_b32_e32 v21, v131
	v_mov_b32_e32 v22, v131
	v_mov_b32_e32 v23, v131
	v_mov_b32_e32 v32, v131
	v_mov_b32_e32 v33, v131
	v_mov_b32_e32 v34, v131
	v_mov_b32_e32 v35, v131
	v_mov_b32_e32 v36, v131
	v_mov_b32_e32 v37, v131
	v_mov_b32_e32 v38, v131
	v_mov_b32_e32 v39, v131
	v_mov_b32_e32 v48, v131
	v_mov_b32_e32 v49, v131
	v_mov_b32_e32 v50, v131
	v_mov_b32_e32 v51, v131
	v_mov_b32_e32 v52, v131
	v_mov_b32_e32 v53, v131
	v_mov_b32_e32 v54, v131
	v_mov_b32_e32 v55, v131
	v_mov_b32_e32 v8, v131
	v_mov_b32_e32 v9, v131
	v_mov_b32_e32 v10, v131
	v_mov_b32_e32 v11, v131
	v_mov_b32_e32 v12, v131
	v_mov_b32_e32 v13, v131
	v_mov_b32_e32 v14, v131
	v_mov_b32_e32 v15, v131
	v_mov_b32_e32 v24, v131
	v_mov_b32_e32 v25, v131
	v_mov_b32_e32 v26, v131
	v_mov_b32_e32 v27, v131
	v_mov_b32_e32 v28, v131
	v_mov_b32_e32 v29, v131
	v_mov_b32_e32 v30, v131
	v_mov_b32_e32 v31, v131
	v_mov_b32_e32 v40, v131
	v_mov_b32_e32 v41, v131
	v_mov_b32_e32 v42, v131
	v_mov_b32_e32 v43, v131
	v_mov_b32_e32 v44, v131
	v_mov_b32_e32 v45, v131
	v_mov_b32_e32 v46, v131
	v_mov_b32_e32 v47, v131
	v_mov_b32_e32 v56, v131
	v_mov_b32_e32 v57, v131
	v_mov_b32_e32 v58, v131
	v_mov_b32_e32 v59, v131
	v_mov_b32_e32 v60, v131
	v_mov_b32_e32 v61, v131
	v_mov_b32_e32 v62, v131
	v_mov_b32_e32 v63, v131
	v_mov_b32_e32 v64, v131
	v_mov_b32_e32 v65, v131
	v_mov_b32_e32 v66, v131
	v_mov_b32_e32 v67, v131
	v_mov_b32_e32 v68, v131
	v_mov_b32_e32 v69, v131
	v_mov_b32_e32 v70, v131
	v_mov_b32_e32 v71, v131
	v_mov_b32_e32 v80, v131
	v_mov_b32_e32 v81, v131
	v_mov_b32_e32 v82, v131
	v_mov_b32_e32 v83, v131
	v_mov_b32_e32 v84, v131
	v_mov_b32_e32 v85, v131
	v_mov_b32_e32 v86, v131
	v_mov_b32_e32 v87, v131
	v_mov_b32_e32 v96, v131
	v_mov_b32_e32 v97, v131
	v_mov_b32_e32 v98, v131
	v_mov_b32_e32 v99, v131
	v_mov_b32_e32 v100, v131
	v_mov_b32_e32 v101, v131
	v_mov_b32_e32 v102, v131
	v_mov_b32_e32 v103, v131
	v_mov_b32_e32 v104, v131
	v_mov_b32_e32 v105, v131
	v_mov_b32_e32 v106, v131
	v_mov_b32_e32 v107, v131
	v_mov_b32_e32 v108, v131
	v_mov_b32_e32 v109, v131
	v_mov_b32_e32 v110, v131
	v_mov_b32_e32 v111, v131
	v_mov_b32_e32 v72, v131
	v_mov_b32_e32 v73, v131
	v_mov_b32_e32 v74, v131
	v_mov_b32_e32 v75, v131
	v_mov_b32_e32 v76, v131
	v_mov_b32_e32 v77, v131
	v_mov_b32_e32 v78, v131
	v_mov_b32_e32 v79, v131
	v_mov_b32_e32 v88, v131
	v_mov_b32_e32 v89, v131
	v_mov_b32_e32 v90, v131
	v_mov_b32_e32 v91, v131
	v_mov_b32_e32 v92, v131
	v_mov_b32_e32 v93, v131
	v_mov_b32_e32 v94, v131
	v_mov_b32_e32 v95, v131
	v_mov_b32_e32 v112, v131
	v_mov_b32_e32 v113, v131
	v_mov_b32_e32 v114, v131
	v_mov_b32_e32 v115, v131
	v_mov_b32_e32 v116, v131
	v_mov_b32_e32 v117, v131
	v_mov_b32_e32 v118, v131
	v_mov_b32_e32 v119, v131
	v_mov_b32_e32 v120, v131
	v_mov_b32_e32 v121, v131
	v_mov_b32_e32 v122, v131
	v_mov_b32_e32 v123, v131
	v_mov_b32_e32 v124, v131
	v_mov_b32_e32 v125, v131
	v_mov_b32_e32 v126, v131
	v_mov_b32_e32 v127, v131
	s_barrier

.LBB0_1330:
	s_add_u32 s6, s22, 0x1c00000
	v_readlane_b32 s48, v246, 0
	s_addc_u32 s7, s23, 0
	s_add_i32 s26, s48, 0x18000
	s_and_b32 s15, s8, 3
	s_add_i32 s41, s26, s12
	s_mov_b64 s[8:9], 0x80
	s_lshl_b32 s24, s11, 13
	s_lshl_b32 s25, s15, 12
	v_lshl_add_u64 v[6:7], v[6:7], 0, s[8:9]
	s_mov_b32 m0, s41
	s_add_i32 s42, s41, 0x2000
	s_add_i32 s43, s35, 0x8000
	s_add_i32 s44, s35, 0xa000
	global_load_lds_dwordx4 v[6:7], off
	v_lshl_add_u64 v[4:5], v[4:5], 0, s[8:9]
	s_mov_b32 m0, s42
	s_add_u32 s22, s18, 0xb0080
	global_load_lds_dwordx4 v[4:5], off
	v_lshl_add_u64 v[2:3], v[2:3], 0, s[8:9]
	s_mov_b32 m0, s43
	s_addc_u32 s23, s19, 0
	s_add_i32 s27, s48, 0x1c000
	global_load_lds_dwordx4 v[2:3], off
	v_lshl_add_u64 v[0:1], v[0:1], 0, s[8:9]
	s_mov_b32 m0, s44
	s_add_i32 s45, s27, s12
	global_load_lds_dwordx4 v[0:1], off
	v_lshl_add_u64 v[0:1], s[22:23], 0, v[138:139]
	s_mov_b32 m0, s45
	s_add_i32 s46, s45, 0x2000
	global_load_lds_dwordx4 v[0:1], off
	v_lshl_add_u64 v[0:1], s[22:23], 0, v[136:137]
	s_mov_b32 m0, s46
	s_sext_i32_i8 s51, s10
	global_load_lds_dwordx4 v[0:1], off
	s_waitcnt vmcnt(8)
	s_barrier
	v_lshrrev_b32_e32 v1, 1, v202
	v_and_b32_e32 v1, 24, v1
	v_and_b32_e32 v0, 15, v202
	v_lshlrev_b32_e32 v2, 1, v1
	v_lshlrev_b32_e32 v3, 2, v202
	v_lshlrev_b32_e32 v4, 6, v202
	s_movk_i32 s10, 0x3c0
	v_lshl_or_b32 v160, s11, 6, v0
	v_lshl_or_b32 v0, v0, 6, v2
	v_and_b32_e32 v3, 32, v3
	v_and_or_b32 v2, v4, s10, v2
	s_waitcnt vmcnt(6)
	v_bitop3_b32 v0, v0, s24, v3 bitop3:0xde
	v_bitop3_b32 v2, s25, v2, v3 bitop3:0xf6
	v_readlane_b32 s10, v246, 1
	v_readlane_b32 s11, v246, 2
	s_ashr_i32 s47, s10, 31
	v_lshl_or_b32 v161, s15, 6, v1
	v_add3_u32 v140, v11, v9, v10
	v_mov_b32_e32 v141, v139
	v_add3_u32 v142, v8, v9, v10
	v_mov_b32_e32 v143, v139
	v_mov_b64_e32 v[144:145], s[0:1]
	v_add_u32_e32 v162, s13, v2
	v_add_u32_e32 v163, s48, v0
	v_add_u32_e32 v164, s14, v2
	v_add_u32_e32 v165, s26, v2
	v_add_u32_e32 v166, s27, v2
	s_barrier
